# cv8 + nt hint on the once-read f32 weight loads of the conversion routine
# baseline (speedup 1.0000x reference)
.Lcv_l0_gd:
	global_load_dwordx4 v[36:39], v2, s[16:17] nt
	global_load_dwordx4 v[40:43], v3, s[16:17] nt
	s_add_u32 s16, s16, s20
	s_addc_u32 s17, s17, 0
	global_load_dwordx4 v[44:47], v2, s[16:17] nt
	global_load_dwordx4 v[48:51], v3, s[16:17] nt
	s_add_u32 s16, s16, s20
	s_addc_u32 s17, s17, 0
	global_load_dwordx4 v[52:55], v2, s[16:17] nt
	global_load_dwordx4 v[56:59], v3, s[16:17] nt
	s_add_u32 s16, s16, s20
	s_addc_u32 s17, s17, 0
	global_load_dwordx4 v[60:63], v2, s[16:17] nt
	global_load_dwordx4 v[64:67], v3, s[16:17] nt
	s_add_u32 s16, s16, s20
	s_addc_u32 s17, s17, 0
	global_load_dwordx4 v[68:71], v2, s[16:17] nt
	global_load_dwordx4 v[72:75], v3, s[16:17] nt
	s_add_u32 s16, s16, s20
	s_addc_u32 s17, s17, 0
	global_load_dwordx4 v[76:79], v2, s[16:17] nt
	global_load_dwordx4 v[80:83], v3, s[16:17] nt
	s_add_u32 s16, s16, s20
	s_addc_u32 s17, s17, 0
	global_load_dwordx4 v[84:87], v2, s[16:17] nt
	global_load_dwordx4 v[88:91], v3, s[16:17] nt
	s_add_u32 s16, s16, s20
	s_addc_u32 s17, s17, 0
	global_load_dwordx4 v[92:95], v2, s[16:17] nt
	global_load_dwordx4 v[96:99], v3, s[16:17] nt
	s_add_u32 s11, s8, s10
	s_cmp_ge_u32 s11, s9
	s_cbranch_scc1 .Lcv_only1
	s_mov_b32 s12, 0
	s_mov_b32 s13, s11
	s_cmp_ge_u32 s13, 0x4180
	s_cbranch_scc0 .Lcv_d1_l
	s_sub_u32 s13, s13, 0x4180
	s_add_u32 s12, s12, 1
	s_cmp_ge_u32 s13, 0x4180
	s_cbranch_scc0 .Lcv_d1_l
	s_sub_u32 s13, s13, 0x4180
	s_add_u32 s12, s12, 1
	s_cmp_ge_u32 s13, 0x4180
	s_cbranch_scc0 .Lcv_d1_l
	s_sub_u32 s13, s13, 0x4180
	s_add_u32 s12, s12, 1

.Lcv_l1_gd:
	global_load_dwordx4 v[100:103], v2, s[16:17] nt
	global_load_dwordx4 v[104:107], v3, s[16:17] nt
	s_add_u32 s16, s16, s20
	s_addc_u32 s17, s17, 0
	global_load_dwordx4 v[108:111], v2, s[16:17] nt
	global_load_dwordx4 v[112:115], v3, s[16:17] nt
	s_add_u32 s16, s16, s20
	s_addc_u32 s17, s17, 0
	global_load_dwordx4 v[116:119], v2, s[16:17] nt
	global_load_dwordx4 v[120:123], v3, s[16:17] nt
	s_add_u32 s16, s16, s20
	s_addc_u32 s17, s17, 0
	global_load_dwordx4 v[124:127], v2, s[16:17] nt
	global_load_dwordx4 v[128:131], v3, s[16:17] nt
	s_add_u32 s16, s16, s20
	s_addc_u32 s17, s17, 0
	global_load_dwordx4 v[132:135], v2, s[16:17] nt
	global_load_dwordx4 v[136:139], v3, s[16:17] nt
	s_add_u32 s16, s16, s20
	s_addc_u32 s17, s17, 0
	global_load_dwordx4 v[140:143], v2, s[16:17] nt
	global_load_dwordx4 v[144:147], v3, s[16:17] nt
	s_add_u32 s16, s16, s20
	s_addc_u32 s17, s17, 0
	global_load_dwordx4 v[148:151], v2, s[16:17] nt
	global_load_dwordx4 v[152:155], v3, s[16:17] nt
	s_add_u32 s16, s16, s20
	s_addc_u32 s17, s17, 0
	global_load_dwordx4 v[156:159], v2, s[16:17] nt
	global_load_dwordx4 v[160:163], v3, s[16:17] nt
	s_waitcnt vmcnt(16)
	s_branch .Lcv_PA

.Lcv_l2A_gd:
	global_load_dwordx4 v[36:39], v2, s[16:17] nt
	global_load_dwordx4 v[40:43], v3, s[16:17] nt
	s_add_u32 s16, s16, s20
	s_addc_u32 s17, s17, 0
	global_load_dwordx4 v[44:47], v2, s[16:17] nt
	global_load_dwordx4 v[48:51], v3, s[16:17] nt
	s_add_u32 s16, s16, s20
	s_addc_u32 s17, s17, 0
	global_load_dwordx4 v[52:55], v2, s[16:17] nt
	global_load_dwordx4 v[56:59], v3, s[16:17] nt
	s_add_u32 s16, s16, s20
	s_addc_u32 s17, s17, 0
	global_load_dwordx4 v[60:63], v2, s[16:17] nt
	global_load_dwordx4 v[64:67], v3, s[16:17] nt
	s_add_u32 s16, s16, s20
	s_addc_u32 s17, s17, 0
	global_load_dwordx4 v[68:71], v2, s[16:17] nt
	global_load_dwordx4 v[72:75], v3, s[16:17] nt
	s_add_u32 s16, s16, s20
	s_addc_u32 s17, s17, 0
	global_load_dwordx4 v[76:79], v2, s[16:17] nt
	global_load_dwordx4 v[80:83], v3, s[16:17] nt
	s_add_u32 s16, s16, s20
	s_addc_u32 s17, s17, 0
	global_load_dwordx4 v[84:87], v2, s[16:17] nt
	global_load_dwordx4 v[88:91], v3, s[16:17] nt
	s_add_u32 s16, s16, s20
	s_addc_u32 s17, s17, 0
	global_load_dwordx4 v[92:95], v2, s[16:17] nt
	global_load_dwordx4 v[96:99], v3, s[16:17] nt

.Lcv_l2B_gd:
	global_load_dwordx4 v[100:103], v2, s[16:17] nt
	global_load_dwordx4 v[104:107], v3, s[16:17] nt
	s_add_u32 s16, s16, s20
	s_addc_u32 s17, s17, 0
	global_load_dwordx4 v[108:111], v2, s[16:17] nt
	global_load_dwordx4 v[112:115], v3, s[16:17] nt
	s_add_u32 s16, s16, s20
	s_addc_u32 s17, s17, 0
	global_load_dwordx4 v[116:119], v2, s[16:17] nt
	global_load_dwordx4 v[120:123], v3, s[16:17] nt
	s_add_u32 s16, s16, s20
	s_addc_u32 s17, s17, 0
	global_load_dwordx4 v[124:127], v2, s[16:17] nt
	global_load_dwordx4 v[128:131], v3, s[16:17] nt
	s_add_u32 s16, s16, s20
	s_addc_u32 s17, s17, 0
	global_load_dwordx4 v[132:135], v2, s[16:17] nt
	global_load_dwordx4 v[136:139], v3, s[16:17] nt
	s_add_u32 s16, s16, s20
	s_addc_u32 s17, s17, 0
	global_load_dwordx4 v[140:143], v2, s[16:17] nt
	global_load_dwordx4 v[144:147], v3, s[16:17] nt
	s_add_u32 s16, s16, s20
	s_addc_u32 s17, s17, 0
	global_load_dwordx4 v[148:151], v2, s[16:17] nt
	global_load_dwordx4 v[152:155], v3, s[16:17] nt
	s_add_u32 s16, s16, s20
	s_addc_u32 s17, s17, 0
	global_load_dwordx4 v[156:159], v2, s[16:17] nt
	global_load_dwordx4 v[160:163], v3, s[16:17] nt

.Lcv_sl1_gd:
	global_load_dwordx4 v[100:103], v2, s[16:17] nt
	global_load_dwordx4 v[104:107], v3, s[16:17] nt
	s_add_u32 s16, s16, s20
	s_addc_u32 s17, s17, 0
	global_load_dwordx4 v[108:111], v2, s[16:17] nt
	global_load_dwordx4 v[112:115], v3, s[16:17] nt
	s_add_u32 s16, s16, s20
	s_addc_u32 s17, s17, 0
	global_load_dwordx4 v[116:119], v2, s[16:17] nt
	global_load_dwordx4 v[120:123], v3, s[16:17] nt
	s_add_u32 s16, s16, s20
	s_addc_u32 s17, s17, 0
	global_load_dwordx4 v[124:127], v2, s[16:17] nt
	global_load_dwordx4 v[128:131], v3, s[16:17] nt
	s_add_u32 s16, s16, s20
	s_addc_u32 s17, s17, 0
	global_load_dwordx4 v[132:135], v2, s[16:17] nt
	global_load_dwordx4 v[136:139], v3, s[16:17] nt
	s_add_u32 s16, s16, s20
	s_addc_u32 s17, s17, 0
	global_load_dwordx4 v[140:143], v2, s[16:17] nt
	global_load_dwordx4 v[144:147], v3, s[16:17] nt
	s_add_u32 s16, s16, s20
	s_addc_u32 s17, s17, 0
	global_load_dwordx4 v[148:151], v2, s[16:17] nt
	global_load_dwordx4 v[152:155], v3, s[16:17] nt
	s_add_u32 s16, s16, s20
	s_addc_u32 s17, s17, 0
	global_load_dwordx4 v[156:159], v2, s[16:17] nt
	global_load_dwordx4 v[160:163], v3, s[16:17] nt
	s_waitcnt vmcnt(16)
	v_pk_mul_f32 v[36:37], v[36:37], v[190:191] op_sel_hi:[1,0]
	v_pk_mul_f32 v[38:39], v[38:39], v[190:191] op_sel_hi:[1,0]
	v_pk_mul_f32 v[40:41], v[40:41], v[190:191] op_sel:[0,1] op_sel_hi:[1,1]
	v_pk_mul_f32 v[42:43], v[42:43], v[190:191] op_sel:[0,1] op_sel_hi:[1,1]
	v_cvt_pk_bf16_f32 v36, v36, v40
	v_cvt_pk_bf16_f32 v37, v37, v41
	v_cvt_pk_bf16_f32 v38, v38, v42
	v_cvt_pk_bf16_f32 v39, v39, v43
	ds_write_b64 v5, v[36:37] offset:0
	ds_write_b64 v5, v[38:39] offset:8
	v_pk_mul_f32 v[44:45], v[44:45], v[192:193] op_sel_hi:[1,0]
	v_pk_mul_f32 v[46:47], v[46:47], v[192:193] op_sel_hi:[1,0]
	v_pk_mul_f32 v[48:49], v[48:49], v[192:193] op_sel:[0,1] op_sel_hi:[1,1]
	v_pk_mul_f32 v[50:51], v[50:51], v[192:193] op_sel:[0,1] op_sel_hi:[1,1]
	v_cvt_pk_bf16_f32 v44, v44, v48
	v_cvt_pk_bf16_f32 v45, v45, v49
	v_cvt_pk_bf16_f32 v46, v46, v50
	v_cvt_pk_bf16_f32 v47, v47, v51
	ds_write_b64 v5, v[44:45] offset:1056
	ds_write_b64 v5, v[46:47] offset:1064
	v_pk_mul_f32 v[52:53], v[52:53], v[194:195] op_sel_hi:[1,0]
	v_pk_mul_f32 v[54:55], v[54:55], v[194:195] op_sel_hi:[1,0]
	v_pk_mul_f32 v[56:57], v[56:57], v[194:195] op_sel:[0,1] op_sel_hi:[1,1]
	v_pk_mul_f32 v[58:59], v[58:59], v[194:195] op_sel:[0,1] op_sel_hi:[1,1]
	v_cvt_pk_bf16_f32 v52, v52, v56
	v_cvt_pk_bf16_f32 v53, v53, v57
	v_cvt_pk_bf16_f32 v54, v54, v58
	v_cvt_pk_bf16_f32 v55, v55, v59
	ds_write_b64 v5, v[52:53] offset:2112
	ds_write_b64 v5, v[54:55] offset:2120
	v_pk_mul_f32 v[60:61], v[60:61], v[196:197] op_sel_hi:[1,0]
	v_pk_mul_f32 v[62:63], v[62:63], v[196:197] op_sel_hi:[1,0]
	v_pk_mul_f32 v[64:65], v[64:65], v[196:197] op_sel:[0,1] op_sel_hi:[1,1]
	v_pk_mul_f32 v[66:67], v[66:67], v[196:197] op_sel:[0,1] op_sel_hi:[1,1]
	v_cvt_pk_bf16_f32 v60, v60, v64
	v_cvt_pk_bf16_f32 v61, v61, v65
	v_cvt_pk_bf16_f32 v62, v62, v66
	v_cvt_pk_bf16_f32 v63, v63, v67
	ds_write_b64 v5, v[60:61] offset:3168
	ds_write_b64 v5, v[62:63] offset:3176
	v_pk_mul_f32 v[68:69], v[68:69], v[198:199] op_sel_hi:[1,0]
	v_pk_mul_f32 v[70:71], v[70:71], v[198:199] op_sel_hi:[1,0]
	v_pk_mul_f32 v[72:73], v[72:73], v[198:199] op_sel:[0,1] op_sel_hi:[1,1]
	v_pk_mul_f32 v[74:75], v[74:75], v[198:199] op_sel:[0,1] op_sel_hi:[1,1]
	v_cvt_pk_bf16_f32 v68, v68, v72
	v_cvt_pk_bf16_f32 v69, v69, v73
	v_cvt_pk_bf16_f32 v70, v70, v74
	v_cvt_pk_bf16_f32 v71, v71, v75
	ds_write_b64 v5, v[68:69] offset:4224
	ds_write_b64 v5, v[70:71] offset:4232
	v_pk_mul_f32 v[76:77], v[76:77], v[200:201] op_sel_hi:[1,0]
	v_pk_mul_f32 v[78:79], v[78:79], v[200:201] op_sel_hi:[1,0]
	v_pk_mul_f32 v[80:81], v[80:81], v[200:201] op_sel:[0,1] op_sel_hi:[1,1]
	v_pk_mul_f32 v[82:83], v[82:83], v[200:201] op_sel:[0,1] op_sel_hi:[1,1]
	v_cvt_pk_bf16_f32 v76, v76, v80
	v_cvt_pk_bf16_f32 v77, v77, v81
	v_cvt_pk_bf16_f32 v78, v78, v82
	v_cvt_pk_bf16_f32 v79, v79, v83
	ds_write_b64 v5, v[76:77] offset:5280
	ds_write_b64 v5, v[78:79] offset:5288
	v_pk_mul_f32 v[84:85], v[84:85], v[202:203] op_sel_hi:[1,0]
	v_pk_mul_f32 v[86:87], v[86:87], v[202:203] op_sel_hi:[1,0]
	v_pk_mul_f32 v[88:89], v[88:89], v[202:203] op_sel:[0,1] op_sel_hi:[1,1]
	v_pk_mul_f32 v[90:91], v[90:91], v[202:203] op_sel:[0,1] op_sel_hi:[1,1]
	v_cvt_pk_bf16_f32 v84, v84, v88
	v_cvt_pk_bf16_f32 v85, v85, v89
	v_cvt_pk_bf16_f32 v86, v86, v90
	v_cvt_pk_bf16_f32 v87, v87, v91
	ds_write_b64 v5, v[84:85] offset:6336
	ds_write_b64 v5, v[86:87] offset:6344
	v_pk_mul_f32 v[92:93], v[92:93], v[204:205] op_sel_hi:[1,0]
	v_pk_mul_f32 v[94:95], v[94:95], v[204:205] op_sel_hi:[1,0]
	v_pk_mul_f32 v[96:97], v[96:97], v[204:205] op_sel:[0,1] op_sel_hi:[1,1]
	v_pk_mul_f32 v[98:99], v[98:99], v[204:205] op_sel:[0,1] op_sel_hi:[1,1]
	v_cvt_pk_bf16_f32 v92, v92, v96
	v_cvt_pk_bf16_f32 v93, v93, v97
	v_cvt_pk_bf16_f32 v94, v94, v98
	v_cvt_pk_bf16_f32 v95, v95, v99
	ds_write_b64 v5, v[92:93] offset:7392
	ds_write_b64 v5, v[94:95] offset:7400
	s_waitcnt lgkmcnt(0)
	ds_read2_b32 v[214:215], v6 offset0:0 offset1:66
	ds_read2_b32 v[216:217], v6 offset0:132 offset1:198
	ds_read2_b32 v[218:219], v6 offset0:8 offset1:74
	ds_read2_b32 v[220:221], v6 offset0:140 offset1:206
	ds_read2_b32 v[222:223], v6 offset0:16 offset1:82
	ds_read2_b32 v[224:225], v6 offset0:148 offset1:214
	ds_read2_b32 v[226:227], v6 offset0:24 offset1:90
	ds_read2_b32 v[228:229], v6 offset0:156 offset1:222
	ds_read2_b32 v[230:231], v6 offset0:32 offset1:98
	ds_read2_b32 v[232:233], v6 offset0:164 offset1:230
	ds_read2_b32 v[234:235], v6 offset0:40 offset1:106
	ds_read2_b32 v[236:237], v6 offset0:172 offset1:238
	ds_read2_b32 v[238:239], v6 offset0:48 offset1:114
	ds_read2_b32 v[240:241], v6 offset0:180 offset1:246
	ds_read2_b32 v[242:243], v6 offset0:56 offset1:122
	ds_read2_b32 v[244:245], v6 offset0:188 offset1:254
	s_waitcnt lgkmcnt(14)
	global_store_dwordx4 v7, v[214:217], s[40:41]
	s_add_u32 s40, s40, s42
	s_addc_u32 s41, s41, 0
	s_waitcnt lgkmcnt(12)
	global_store_dwordx4 v7, v[218:221], s[40:41]
	s_add_u32 s40, s40, s42
	s_addc_u32 s41, s41, 0
	s_waitcnt lgkmcnt(10)
	global_store_dwordx4 v7, v[222:225], s[40:41]
	s_add_u32 s40, s40, s42
	s_addc_u32 s41, s41, 0
	s_waitcnt lgkmcnt(8)
	global_store_dwordx4 v7, v[226:229], s[40:41]
	s_add_u32 s40, s40, s42
	s_addc_u32 s41, s41, 0
	s_waitcnt lgkmcnt(6)
	global_store_dwordx4 v7, v[230:233], s[40:41]
	s_add_u32 s40, s40, s42
	s_addc_u32 s41, s41, 0
	s_waitcnt lgkmcnt(4)
	global_store_dwordx4 v7, v[234:237], s[40:41]
	s_add_u32 s40, s40, s42
	s_addc_u32 s41, s41, 0
	s_waitcnt lgkmcnt(2)
	global_store_dwordx4 v7, v[238:241], s[40:41]
	s_add_u32 s40, s40, s42
	s_addc_u32 s41, s41, 0
	s_waitcnt lgkmcnt(0)
	global_store_dwordx4 v7, v[242:245], s[40:41]
	s_mov_b32 s8, s11
	s_add_u32 s11, s8, s10
	s_cmp_ge_u32 s11, s9
	s_cbranch_scc1 .Lcv_slastB
	s_mov_b32 s12, 0
	s_mov_b32 s13, s11
	s_cmp_ge_u32 s13, 0x4180
	s_cbranch_scc0 .Lcv_sd2_l
	s_sub_u32 s13, s13, 0x4180
	s_add_u32 s12, s12, 1
	s_cmp_ge_u32 s13, 0x4180
	s_cbranch_scc0 .Lcv_sd2_l
	s_sub_u32 s13, s13, 0x4180
	s_add_u32 s12, s12, 1
	s_cmp_ge_u32 s13, 0x4180
	s_cbranch_scc0 .Lcv_sd2_l
	s_sub_u32 s13, s13, 0x4180
	s_add_u32 s12, s12, 1

.Lcv_sl2_gd:
	global_load_dwordx4 v[36:39], v2, s[16:17] nt
	global_load_dwordx4 v[40:43], v3, s[16:17] nt
	s_add_u32 s16, s16, s20
	s_addc_u32 s17, s17, 0
	global_load_dwordx4 v[44:47], v2, s[16:17] nt
	global_load_dwordx4 v[48:51], v3, s[16:17] nt
	s_add_u32 s16, s16, s20
	s_addc_u32 s17, s17, 0
	global_load_dwordx4 v[52:55], v2, s[16:17] nt
	global_load_dwordx4 v[56:59], v3, s[16:17] nt
	s_add_u32 s16, s16, s20
	s_addc_u32 s17, s17, 0
	global_load_dwordx4 v[60:63], v2, s[16:17] nt
	global_load_dwordx4 v[64:67], v3, s[16:17] nt
	s_add_u32 s16, s16, s20
	s_addc_u32 s17, s17, 0
	global_load_dwordx4 v[68:71], v2, s[16:17] nt
	global_load_dwordx4 v[72:75], v3, s[16:17] nt
	s_add_u32 s16, s16, s20
	s_addc_u32 s17, s17, 0
	global_load_dwordx4 v[76:79], v2, s[16:17] nt
	global_load_dwordx4 v[80:83], v3, s[16:17] nt
	s_add_u32 s16, s16, s20
	s_addc_u32 s17, s17, 0
	global_load_dwordx4 v[84:87], v2, s[16:17] nt
	global_load_dwordx4 v[88:91], v3, s[16:17] nt
	s_add_u32 s16, s16, s20
	s_addc_u32 s17, s17, 0
	global_load_dwordx4 v[92:95], v2, s[16:17] nt
	global_load_dwordx4 v[96:99], v3, s[16:17] nt
	s_waitcnt vmcnt(16)
	v_pk_mul_f32 v[100:101], v[100:101], v[18:19] op_sel_hi:[1,0]
	v_pk_mul_f32 v[102:103], v[102:103], v[18:19] op_sel_hi:[1,0]
	v_pk_mul_f32 v[104:105], v[104:105], v[18:19] op_sel:[0,1] op_sel_hi:[1,1]
	v_pk_mul_f32 v[106:107], v[106:107], v[18:19] op_sel:[0,1] op_sel_hi:[1,1]
	v_cvt_pk_bf16_f32 v100, v100, v104
	v_cvt_pk_bf16_f32 v101, v101, v105
	v_cvt_pk_bf16_f32 v102, v102, v106
	v_cvt_pk_bf16_f32 v103, v103, v107
	ds_write_b64 v5, v[100:101] offset:0
	ds_write_b64 v5, v[102:103] offset:8
	v_pk_mul_f32 v[108:109], v[108:109], v[20:21] op_sel_hi:[1,0]
	v_pk_mul_f32 v[110:111], v[110:111], v[20:21] op_sel_hi:[1,0]
	v_pk_mul_f32 v[112:113], v[112:113], v[20:21] op_sel:[0,1] op_sel_hi:[1,1]
	v_pk_mul_f32 v[114:115], v[114:115], v[20:21] op_sel:[0,1] op_sel_hi:[1,1]
	v_cvt_pk_bf16_f32 v108, v108, v112
	v_cvt_pk_bf16_f32 v109, v109, v113
	v_cvt_pk_bf16_f32 v110, v110, v114
	v_cvt_pk_bf16_f32 v111, v111, v115
	ds_write_b64 v5, v[108:109] offset:1056
	ds_write_b64 v5, v[110:111] offset:1064
	v_pk_mul_f32 v[116:117], v[116:117], v[22:23] op_sel_hi:[1,0]
	v_pk_mul_f32 v[118:119], v[118:119], v[22:23] op_sel_hi:[1,0]
	v_pk_mul_f32 v[120:121], v[120:121], v[22:23] op_sel:[0,1] op_sel_hi:[1,1]
	v_pk_mul_f32 v[122:123], v[122:123], v[22:23] op_sel:[0,1] op_sel_hi:[1,1]
	v_cvt_pk_bf16_f32 v116, v116, v120
	v_cvt_pk_bf16_f32 v117, v117, v121
	v_cvt_pk_bf16_f32 v118, v118, v122
	v_cvt_pk_bf16_f32 v119, v119, v123
	ds_write_b64 v5, v[116:117] offset:2112
	ds_write_b64 v5, v[118:119] offset:2120
	v_pk_mul_f32 v[124:125], v[124:125], v[24:25] op_sel_hi:[1,0]
	v_pk_mul_f32 v[126:127], v[126:127], v[24:25] op_sel_hi:[1,0]
	v_pk_mul_f32 v[128:129], v[128:129], v[24:25] op_sel:[0,1] op_sel_hi:[1,1]
	v_pk_mul_f32 v[130:131], v[130:131], v[24:25] op_sel:[0,1] op_sel_hi:[1,1]
	v_cvt_pk_bf16_f32 v124, v124, v128
	v_cvt_pk_bf16_f32 v125, v125, v129
	v_cvt_pk_bf16_f32 v126, v126, v130
	v_cvt_pk_bf16_f32 v127, v127, v131
	ds_write_b64 v5, v[124:125] offset:3168
	ds_write_b64 v5, v[126:127] offset:3176
	v_pk_mul_f32 v[132:133], v[132:133], v[26:27] op_sel_hi:[1,0]
	v_pk_mul_f32 v[134:135], v[134:135], v[26:27] op_sel_hi:[1,0]
	v_pk_mul_f32 v[136:137], v[136:137], v[26:27] op_sel:[0,1] op_sel_hi:[1,1]
	v_pk_mul_f32 v[138:139], v[138:139], v[26:27] op_sel:[0,1] op_sel_hi:[1,1]
	v_cvt_pk_bf16_f32 v132, v132, v136
	v_cvt_pk_bf16_f32 v133, v133, v137
	v_cvt_pk_bf16_f32 v134, v134, v138
	v_cvt_pk_bf16_f32 v135, v135, v139
	ds_write_b64 v5, v[132:133] offset:4224
	ds_write_b64 v5, v[134:135] offset:4232
	v_pk_mul_f32 v[140:141], v[140:141], v[28:29] op_sel_hi:[1,0]
	v_pk_mul_f32 v[142:143], v[142:143], v[28:29] op_sel_hi:[1,0]
	v_pk_mul_f32 v[144:145], v[144:145], v[28:29] op_sel:[0,1] op_sel_hi:[1,1]
	v_pk_mul_f32 v[146:147], v[146:147], v[28:29] op_sel:[0,1] op_sel_hi:[1,1]
	v_cvt_pk_bf16_f32 v140, v140, v144
	v_cvt_pk_bf16_f32 v141, v141, v145
	v_cvt_pk_bf16_f32 v142, v142, v146
	v_cvt_pk_bf16_f32 v143, v143, v147
	ds_write_b64 v5, v[140:141] offset:5280
	ds_write_b64 v5, v[142:143] offset:5288
	v_pk_mul_f32 v[148:149], v[148:149], v[30:31] op_sel_hi:[1,0]
	v_pk_mul_f32 v[150:151], v[150:151], v[30:31] op_sel_hi:[1,0]
	v_pk_mul_f32 v[152:153], v[152:153], v[30:31] op_sel:[0,1] op_sel_hi:[1,1]
	v_pk_mul_f32 v[154:155], v[154:155], v[30:31] op_sel:[0,1] op_sel_hi:[1,1]
	v_cvt_pk_bf16_f32 v148, v148, v152
	v_cvt_pk_bf16_f32 v149, v149, v153
	v_cvt_pk_bf16_f32 v150, v150, v154
	v_cvt_pk_bf16_f32 v151, v151, v155
	ds_write_b64 v5, v[148:149] offset:6336
	ds_write_b64 v5, v[150:151] offset:6344
	v_pk_mul_f32 v[156:157], v[156:157], v[32:33] op_sel_hi:[1,0]
	v_pk_mul_f32 v[158:159], v[158:159], v[32:33] op_sel_hi:[1,0]
	v_pk_mul_f32 v[160:161], v[160:161], v[32:33] op_sel:[0,1] op_sel_hi:[1,1]
	v_pk_mul_f32 v[162:163], v[162:163], v[32:33] op_sel:[0,1] op_sel_hi:[1,1]
	v_cvt_pk_bf16_f32 v156, v156, v160
	v_cvt_pk_bf16_f32 v157, v157, v161
	v_cvt_pk_bf16_f32 v158, v158, v162
	v_cvt_pk_bf16_f32 v159, v159, v163
	ds_write_b64 v5, v[156:157] offset:7392
	ds_write_b64 v5, v[158:159] offset:7400
	s_waitcnt lgkmcnt(0)
	ds_read2_b32 v[214:215], v6 offset0:0 offset1:66
	ds_read2_b32 v[216:217], v6 offset0:132 offset1:198
	ds_read2_b32 v[218:219], v6 offset0:8 offset1:74
	ds_read2_b32 v[220:221], v6 offset0:140 offset1:206
	ds_read2_b32 v[222:223], v6 offset0:16 offset1:82
	ds_read2_b32 v[224:225], v6 offset0:148 offset1:214
	ds_read2_b32 v[226:227], v6 offset0:24 offset1:90
	ds_read2_b32 v[228:229], v6 offset0:156 offset1:222
	ds_read2_b32 v[230:231], v6 offset0:32 offset1:98
	ds_read2_b32 v[232:233], v6 offset0:164 offset1:230
	ds_read2_b32 v[234:235], v6 offset0:40 offset1:106
	ds_read2_b32 v[236:237], v6 offset0:172 offset1:238
	ds_read2_b32 v[238:239], v6 offset0:48 offset1:114
	ds_read2_b32 v[240:241], v6 offset0:180 offset1:246
	ds_read2_b32 v[242:243], v6 offset0:56 offset1:122
	ds_read2_b32 v[244:245], v6 offset0:188 offset1:254
	s_waitcnt lgkmcnt(14)
	global_store_dwordx4 v12, v[214:217], s[44:45]
	s_add_u32 s44, s44, s46
	s_addc_u32 s45, s45, 0
	s_waitcnt lgkmcnt(12)
	global_store_dwordx4 v12, v[218:221], s[44:45]
	s_add_u32 s44, s44, s46
	s_addc_u32 s45, s45, 0
	s_waitcnt lgkmcnt(10)
	global_store_dwordx4 v12, v[222:225], s[44:45]
	s_add_u32 s44, s44, s46
	s_addc_u32 s45, s45, 0
	s_waitcnt lgkmcnt(8)
	global_store_dwordx4 v12, v[226:229], s[44:45]
	s_add_u32 s44, s44, s46
	s_addc_u32 s45, s45, 0
	s_waitcnt lgkmcnt(6)
	global_store_dwordx4 v12, v[230:233], s[44:45]
	s_add_u32 s44, s44, s46
	s_addc_u32 s45, s45, 0
	s_waitcnt lgkmcnt(4)
	global_store_dwordx4 v12, v[234:237], s[44:45]
	s_add_u32 s44, s44, s46
	s_addc_u32 s45, s45, 0
	s_waitcnt lgkmcnt(2)
	global_store_dwordx4 v12, v[238:241], s[44:45]
	s_add_u32 s44, s44, s46
	s_addc_u32 s45, s45, 0
	s_waitcnt lgkmcnt(0)
	global_store_dwordx4 v12, v[242:245], s[44:45]
	s_mov_b32 s8, s11
	s_branch .Lcv_sloop
